# RG-LRU (one mode): 16 serialized conv-tile loads issued together into separate registers, single vmcnt wait, then the LDS writes
# speedup vs baseline: 1.0150x; 1.0066x over previous
; DI int get_tid() { int t = threadIdx.x; asm volatile("" : "+v"(t)); return t; }
; DI float bf2f(u16 v) { return __uint_as_float(((unsigned)v) << 16); }
; DI void lru_job(const Params& P, int layer, int b, int chunk, int blk, int mode, char* smem, const LruConst& C) {
;     ...
;   const int tid = get_tid(), d = tid & 63, tq = tid >> 6;
;   const int seg_lo = chunk < 4 ? 0 : CTX, seg_hi = chunk < 4 ? CTX : TB, p0 = chunk * 64;
;   const int ch = blk * 64 + d;
;   const u16* XA = (const u16*)(P.ws + OFF_XA);
;   const int lane = tid & 63, r = lane & 31, h = lane >> 5, wdir = tq >> 1, wmi = tq & 1;
;   __syncthreads();
; #pragma unroll
;   for (int it = 0; it < 17; ++it) {
;     int idx = tid + it * 256;
;     int rr = idx >> 6, dd = idx & 63, pp = p0 - 1 + rr;
;     if (idx < 67 * 64) xs[idx] = (pp >= seg_lo && pp < seg_hi) ? bf2f(XA[((size_t)b * TB + pp) * 512 + blk * 64 + dd]) : 0.f;
;   }
.LBB0_860:
	s_ashr_i32 s6, s12, 3
	s_mul_hi_i32 s7, s6, 0x78787879
	s_lshr_b32 s8, s7, 31
	s_ashr_i32 s7, s7, 5
	s_add_i32 s7, s7, s8
	s_mulk_i32 s7, 0x44
	s_sub_i32 s14, s6, s7
	s_mul_hi_i32 s6, s12, 0x78787879
	s_lshr_b32 s7, s6, 31
	s_ashr_i32 s15, s6, 8
	s_add_i32 s15, s15, s7
	s_cmp_lt_i32 s14, 4
	s_movk_i32 s6, 0x100
	s_cselect_b32 s16, 0, 0x100
	s_cselect_b32 s17, s6, 0x1100
	s_lshl_b32 s22, s14, 6
	s_waitcnt vmcnt(2)
	v_mov_b32_e32 v131, v171
	s_add_i32 s22, s22, -1
	s_lshl_b64 s[8:9], s[4:5], 1
	v_readlane_b32 s10, v251, 18
	v_readlane_b32 s11, v251, 19
	v_and_b32_e32 v141, 63, v131
	s_add_u32 s8, s10, s8
	s_addc_u32 s9, s11, s9
	s_waitcnt vmcnt(0)
	v_lshlrev_b32_e32 v168, 1, v141
	v_lshl_add_u64 v[0:1], s[8:9], 0, v[168:169]
	s_movk_i32 s8, 0x10c0
	s_mul_hi_i32 s7, s15, 0x1100
	s_mul_i32 s6, s15, 0x1100
	v_ashrrev_i32_e32 v130, 6, v131
	v_cmp_gt_i32_e32 vcc, s8, v131
	s_barrier
	s_and_saveexec_b64 s[10:11], vcc
	s_cbranch_execz .LBB0_864
	v_add_u32_e32 v2, s22, v130
	v_cmp_le_i32_e32 vcc, s16, v2
	v_cmp_gt_i32_e64 s[8:9], s17, v2
	s_and_b64 s[24:25], vcc, s[8:9]
	v_mov_b32_e32 v4, 0
	s_and_saveexec_b64 s[8:9], s[24:25]
	s_cbranch_execz .LBB0_863
	v_mov_b32_e32 v3, v169
	v_lshl_add_u64 v[2:3], s[6:7], 0, v[2:3]
	v_lshlrev_b64 v[2:3], 10, v[2:3]
	v_lshl_add_u64 v[2:3], v[0:1], 0, v[2:3]
	global_load_ushort v4, v[2:3], off

; DI float bf2f(u16 v) { return __uint_as_float(((unsigned)v) << 16); }
; DI void lru_job(const Params& P, int layer, int b, int chunk, int blk, int mode, char* smem, const LruConst& C) {
;     ...
;   for (int it = 0; it < 17; ++it) {
;     int idx = tid + it * 256;
;     int rr = idx >> 6, dd = idx & 63, pp = p0 - 1 + rr;
;     if (idx < 67 * 64) xs[idx] = (pp >= seg_lo && pp < seg_hi) ? bf2f(XA[((size_t)b * TB + pp) * 512 + blk * 64 + dd]) : 0.f;
;   }
.LBB0_864:
	s_or_b64 exec, exec, s[10:11]
	s_movk_i32 s8, 0xfc0
	v_cmp_gt_i32_e32 vcc, s8, v131
	s_and_saveexec_b64 s[10:11], vcc
	s_cbranch_execz .LBB0_868
	v_add_u32_e32 v2, 0x100, v131
	v_ashrrev_i32_e32 v2, 6, v2
	v_add_u32_e32 v2, s22, v2
	v_cmp_le_i32_e32 vcc, s16, v2
	v_cmp_gt_i32_e64 s[8:9], s17, v2
	s_and_b64 s[24:25], vcc, s[8:9]
	v_mov_b32_e32 v5, 0
	s_and_saveexec_b64 s[8:9], s[24:25]
	s_cbranch_execz .LBB0_867
	v_mov_b32_e32 v3, v169
	v_lshl_add_u64 v[2:3], s[6:7], 0, v[2:3]
	v_lshlrev_b64 v[2:3], 10, v[2:3]
	v_lshl_add_u64 v[2:3], v[0:1], 0, v[2:3]
	global_load_ushort v5, v[2:3], off

; DI float bf2f(u16 v) { return __uint_as_float(((unsigned)v) << 16); }
; DI void lru_job(const Params& P, int layer, int b, int chunk, int blk, int mode, char* smem, const LruConst& C) {
;     ...
;   for (int it = 0; it < 17; ++it) {
;     int idx = tid + it * 256;
;     int rr = idx >> 6, dd = idx & 63, pp = p0 - 1 + rr;
;     if (idx < 67 * 64) xs[idx] = (pp >= seg_lo && pp < seg_hi) ? bf2f(XA[((size_t)b * TB + pp) * 512 + blk * 64 + dd]) : 0.f;
;   }
.LBB0_868:
	s_or_b64 exec, exec, s[10:11]
	s_movk_i32 s8, 0xec0
	v_cmp_gt_i32_e32 vcc, s8, v131
	s_and_saveexec_b64 s[10:11], vcc
	s_cbranch_execz .LBB0_872
	v_add_u32_e32 v2, 0x200, v131
	v_ashrrev_i32_e32 v2, 6, v2
	v_add_u32_e32 v2, s22, v2
	v_cmp_le_i32_e32 vcc, s16, v2
	v_cmp_gt_i32_e64 s[8:9], s17, v2
	s_and_b64 s[24:25], vcc, s[8:9]
	v_mov_b32_e32 v6, 0
	s_and_saveexec_b64 s[8:9], s[24:25]
	s_cbranch_execz .LBB0_871
	v_mov_b32_e32 v3, v169
	v_lshl_add_u64 v[2:3], s[6:7], 0, v[2:3]
	v_lshlrev_b64 v[2:3], 10, v[2:3]
	v_lshl_add_u64 v[2:3], v[0:1], 0, v[2:3]
	global_load_ushort v6, v[2:3], off

; DI float bf2f(u16 v) { return __uint_as_float(((unsigned)v) << 16); }
; DI void lru_job(const Params& P, int layer, int b, int chunk, int blk, int mode, char* smem, const LruConst& C) {
;     ...
;   for (int it = 0; it < 17; ++it) {
;     int idx = tid + it * 256;
;     int rr = idx >> 6, dd = idx & 63, pp = p0 - 1 + rr;
;     if (idx < 67 * 64) xs[idx] = (pp >= seg_lo && pp < seg_hi) ? bf2f(XA[((size_t)b * TB + pp) * 512 + blk * 64 + dd]) : 0.f;
;   }
.LBB0_872:
	s_or_b64 exec, exec, s[10:11]
	s_movk_i32 s8, 0xdc0
	v_cmp_gt_i32_e32 vcc, s8, v131
	s_and_saveexec_b64 s[10:11], vcc
	s_cbranch_execz .LBB0_876
	v_add_u32_e32 v2, 0x300, v131
	v_ashrrev_i32_e32 v2, 6, v2
	v_add_u32_e32 v2, s22, v2
	v_cmp_le_i32_e32 vcc, s16, v2
	v_cmp_gt_i32_e64 s[8:9], s17, v2
	s_and_b64 s[24:25], vcc, s[8:9]
	v_mov_b32_e32 v7, 0
	s_and_saveexec_b64 s[8:9], s[24:25]
	s_cbranch_execz .LBB0_875
	v_mov_b32_e32 v3, v169
	v_lshl_add_u64 v[2:3], s[6:7], 0, v[2:3]
	v_lshlrev_b64 v[2:3], 10, v[2:3]
	v_lshl_add_u64 v[2:3], v[0:1], 0, v[2:3]
	global_load_ushort v7, v[2:3], off

; DI float bf2f(u16 v) { return __uint_as_float(((unsigned)v) << 16); }
; DI void lru_job(const Params& P, int layer, int b, int chunk, int blk, int mode, char* smem, const LruConst& C) {
;     ...
;   for (int it = 0; it < 17; ++it) {
;     int idx = tid + it * 256;
;     int rr = idx >> 6, dd = idx & 63, pp = p0 - 1 + rr;
;     if (idx < 67 * 64) xs[idx] = (pp >= seg_lo && pp < seg_hi) ? bf2f(XA[((size_t)b * TB + pp) * 512 + blk * 64 + dd]) : 0.f;
;   }
.LBB0_876:
	s_or_b64 exec, exec, s[10:11]
	s_movk_i32 s8, 0xcc0
	v_cmp_gt_i32_e32 vcc, s8, v131
	s_and_saveexec_b64 s[10:11], vcc
	s_cbranch_execz .LBB0_880
	v_add_u32_e32 v2, 0x400, v131
	v_ashrrev_i32_e32 v2, 6, v2
	v_add_u32_e32 v2, s22, v2
	v_cmp_le_i32_e32 vcc, s16, v2
	v_cmp_gt_i32_e64 s[8:9], s17, v2
	s_and_b64 s[24:25], vcc, s[8:9]
	v_mov_b32_e32 v8, 0
	s_and_saveexec_b64 s[8:9], s[24:25]
	s_cbranch_execz .LBB0_879
	v_mov_b32_e32 v3, v169
	v_lshl_add_u64 v[2:3], s[6:7], 0, v[2:3]
	v_lshlrev_b64 v[2:3], 10, v[2:3]
	v_lshl_add_u64 v[2:3], v[0:1], 0, v[2:3]
	global_load_ushort v8, v[2:3], off

; DI float bf2f(u16 v) { return __uint_as_float(((unsigned)v) << 16); }
; DI void lru_job(const Params& P, int layer, int b, int chunk, int blk, int mode, char* smem, const LruConst& C) {
;     ...
;   for (int it = 0; it < 17; ++it) {
;     int idx = tid + it * 256;
;     int rr = idx >> 6, dd = idx & 63, pp = p0 - 1 + rr;
;     if (idx < 67 * 64) xs[idx] = (pp >= seg_lo && pp < seg_hi) ? bf2f(XA[((size_t)b * TB + pp) * 512 + blk * 64 + dd]) : 0.f;
;   }
.LBB0_880:
	s_or_b64 exec, exec, s[10:11]
	s_movk_i32 s8, 0xbc0
	v_cmp_gt_i32_e32 vcc, s8, v131
	s_and_saveexec_b64 s[10:11], vcc
	s_cbranch_execz .LBB0_884
	v_add_u32_e32 v2, 0x500, v131
	v_ashrrev_i32_e32 v2, 6, v2
	v_add_u32_e32 v2, s22, v2
	v_cmp_le_i32_e32 vcc, s16, v2
	v_cmp_gt_i32_e64 s[8:9], s17, v2
	s_and_b64 s[24:25], vcc, s[8:9]
	v_mov_b32_e32 v9, 0
	s_and_saveexec_b64 s[8:9], s[24:25]
	s_cbranch_execz .LBB0_883
	v_mov_b32_e32 v3, v169
	v_lshl_add_u64 v[2:3], s[6:7], 0, v[2:3]
	v_lshlrev_b64 v[2:3], 10, v[2:3]
	v_lshl_add_u64 v[2:3], v[0:1], 0, v[2:3]
	global_load_ushort v9, v[2:3], off

; DI float bf2f(u16 v) { return __uint_as_float(((unsigned)v) << 16); }
; DI void lru_job(const Params& P, int layer, int b, int chunk, int blk, int mode, char* smem, const LruConst& C) {
;     ...
;   for (int it = 0; it < 17; ++it) {
;     int idx = tid + it * 256;
;     int rr = idx >> 6, dd = idx & 63, pp = p0 - 1 + rr;
;     if (idx < 67 * 64) xs[idx] = (pp >= seg_lo && pp < seg_hi) ? bf2f(XA[((size_t)b * TB + pp) * 512 + blk * 64 + dd]) : 0.f;
;   }
.LBB0_884:
	s_or_b64 exec, exec, s[10:11]
	s_movk_i32 s8, 0xac0
	v_cmp_gt_i32_e32 vcc, s8, v131
	s_and_saveexec_b64 s[10:11], vcc
	s_cbranch_execz .LBB0_888
	v_add_u32_e32 v2, 0x600, v131
	v_ashrrev_i32_e32 v2, 6, v2
	v_add_u32_e32 v2, s22, v2
	v_cmp_le_i32_e32 vcc, s16, v2
	v_cmp_gt_i32_e64 s[8:9], s17, v2
	s_and_b64 s[24:25], vcc, s[8:9]
	v_mov_b32_e32 v10, 0
	s_and_saveexec_b64 s[8:9], s[24:25]
	s_cbranch_execz .LBB0_887
	v_mov_b32_e32 v3, v169
	v_lshl_add_u64 v[2:3], s[6:7], 0, v[2:3]
	v_lshlrev_b64 v[2:3], 10, v[2:3]
	v_lshl_add_u64 v[2:3], v[0:1], 0, v[2:3]
	global_load_ushort v10, v[2:3], off

; DI float bf2f(u16 v) { return __uint_as_float(((unsigned)v) << 16); }
; DI void lru_job(const Params& P, int layer, int b, int chunk, int blk, int mode, char* smem, const LruConst& C) {
;     ...
;   for (int it = 0; it < 17; ++it) {
;     int idx = tid + it * 256;
;     int rr = idx >> 6, dd = idx & 63, pp = p0 - 1 + rr;
;     if (idx < 67 * 64) xs[idx] = (pp >= seg_lo && pp < seg_hi) ? bf2f(XA[((size_t)b * TB + pp) * 512 + blk * 64 + dd]) : 0.f;
;   }
.LBB0_888:
	s_or_b64 exec, exec, s[10:11]
	s_movk_i32 s8, 0x9c0
	v_cmp_gt_i32_e32 vcc, s8, v131
	s_and_saveexec_b64 s[10:11], vcc
	s_cbranch_execz .LBB0_892
	v_add_u32_e32 v2, 0x700, v131
	v_ashrrev_i32_e32 v2, 6, v2
	v_add_u32_e32 v2, s22, v2
	v_cmp_le_i32_e32 vcc, s16, v2
	v_cmp_gt_i32_e64 s[8:9], s17, v2
	s_and_b64 s[24:25], vcc, s[8:9]
	v_mov_b32_e32 v11, 0
	s_and_saveexec_b64 s[8:9], s[24:25]
	s_cbranch_execz .LBB0_891
	v_mov_b32_e32 v3, v169
	v_lshl_add_u64 v[2:3], s[6:7], 0, v[2:3]
	v_lshlrev_b64 v[2:3], 10, v[2:3]
	v_lshl_add_u64 v[2:3], v[0:1], 0, v[2:3]
	global_load_ushort v11, v[2:3], off

; DI float bf2f(u16 v) { return __uint_as_float(((unsigned)v) << 16); }
; DI void lru_job(const Params& P, int layer, int b, int chunk, int blk, int mode, char* smem, const LruConst& C) {
;     ...
;   for (int it = 0; it < 17; ++it) {
;     int idx = tid + it * 256;
;     int rr = idx >> 6, dd = idx & 63, pp = p0 - 1 + rr;
;     if (idx < 67 * 64) xs[idx] = (pp >= seg_lo && pp < seg_hi) ? bf2f(XA[((size_t)b * TB + pp) * 512 + blk * 64 + dd]) : 0.f;
;   }
.LBB0_892:
	s_or_b64 exec, exec, s[10:11]
	s_movk_i32 s8, 0x8c0
	v_cmp_gt_i32_e32 vcc, s8, v131
	s_and_saveexec_b64 s[10:11], vcc
	s_cbranch_execz .LBB0_896
	v_add_u32_e32 v2, 0x800, v131
	v_ashrrev_i32_e32 v2, 6, v2
	v_add_u32_e32 v2, s22, v2
	v_cmp_le_i32_e32 vcc, s16, v2
	v_cmp_gt_i32_e64 s[8:9], s17, v2
	s_and_b64 s[24:25], vcc, s[8:9]
	v_mov_b32_e32 v12, 0
	s_and_saveexec_b64 s[8:9], s[24:25]
	s_cbranch_execz .LBB0_895
	v_mov_b32_e32 v3, v169
	v_lshl_add_u64 v[2:3], s[6:7], 0, v[2:3]
	v_lshlrev_b64 v[2:3], 10, v[2:3]
	v_lshl_add_u64 v[2:3], v[0:1], 0, v[2:3]
	global_load_ushort v12, v[2:3], off

; DI float bf2f(u16 v) { return __uint_as_float(((unsigned)v) << 16); }
; DI void lru_job(const Params& P, int layer, int b, int chunk, int blk, int mode, char* smem, const LruConst& C) {
;     ...
;   for (int it = 0; it < 17; ++it) {
;     int idx = tid + it * 256;
;     int rr = idx >> 6, dd = idx & 63, pp = p0 - 1 + rr;
;     if (idx < 67 * 64) xs[idx] = (pp >= seg_lo && pp < seg_hi) ? bf2f(XA[((size_t)b * TB + pp) * 512 + blk * 64 + dd]) : 0.f;
;   }
.LBB0_896:
	s_or_b64 exec, exec, s[10:11]
	s_movk_i32 s8, 0x7c0
	v_cmp_gt_i32_e32 vcc, s8, v131
	s_and_saveexec_b64 s[10:11], vcc
	s_cbranch_execz .LBB0_900
	v_add_u32_e32 v2, 0x900, v131
	v_ashrrev_i32_e32 v2, 6, v2
	v_add_u32_e32 v2, s22, v2
	v_cmp_le_i32_e32 vcc, s16, v2
	v_cmp_gt_i32_e64 s[8:9], s17, v2
	s_and_b64 s[24:25], vcc, s[8:9]
	v_mov_b32_e32 v13, 0
	s_and_saveexec_b64 s[8:9], s[24:25]
	s_cbranch_execz .LBB0_899
	v_mov_b32_e32 v3, v169
	v_lshl_add_u64 v[2:3], s[6:7], 0, v[2:3]
	v_lshlrev_b64 v[2:3], 10, v[2:3]
	v_lshl_add_u64 v[2:3], v[0:1], 0, v[2:3]
	global_load_ushort v13, v[2:3], off

; DI float bf2f(u16 v) { return __uint_as_float(((unsigned)v) << 16); }
; DI void lru_job(const Params& P, int layer, int b, int chunk, int blk, int mode, char* smem, const LruConst& C) {
;     ...
;   for (int it = 0; it < 17; ++it) {
;     int idx = tid + it * 256;
;     int rr = idx >> 6, dd = idx & 63, pp = p0 - 1 + rr;
;     if (idx < 67 * 64) xs[idx] = (pp >= seg_lo && pp < seg_hi) ? bf2f(XA[((size_t)b * TB + pp) * 512 + blk * 64 + dd]) : 0.f;
;   }
.LBB0_900:
	s_or_b64 exec, exec, s[10:11]
	s_movk_i32 s8, 0x6c0
	v_cmp_gt_i32_e32 vcc, s8, v131
	s_and_saveexec_b64 s[10:11], vcc
	s_cbranch_execz .LBB0_904
	v_add_u32_e32 v2, 0xa00, v131
	v_ashrrev_i32_e32 v2, 6, v2
	v_add_u32_e32 v2, s22, v2
	v_cmp_le_i32_e32 vcc, s16, v2
	v_cmp_gt_i32_e64 s[8:9], s17, v2
	s_and_b64 s[24:25], vcc, s[8:9]
	v_mov_b32_e32 v14, 0
	s_and_saveexec_b64 s[8:9], s[24:25]
	s_cbranch_execz .LBB0_903
	v_mov_b32_e32 v3, v169
	v_lshl_add_u64 v[2:3], s[6:7], 0, v[2:3]
	v_lshlrev_b64 v[2:3], 10, v[2:3]
	v_lshl_add_u64 v[2:3], v[0:1], 0, v[2:3]
	global_load_ushort v14, v[2:3], off

; DI float bf2f(u16 v) { return __uint_as_float(((unsigned)v) << 16); }
; DI void lru_job(const Params& P, int layer, int b, int chunk, int blk, int mode, char* smem, const LruConst& C) {
;     ...
;   for (int it = 0; it < 17; ++it) {
;     int idx = tid + it * 256;
;     int rr = idx >> 6, dd = idx & 63, pp = p0 - 1 + rr;
;     if (idx < 67 * 64) xs[idx] = (pp >= seg_lo && pp < seg_hi) ? bf2f(XA[((size_t)b * TB + pp) * 512 + blk * 64 + dd]) : 0.f;
;   }
.LBB0_904:
	s_or_b64 exec, exec, s[10:11]
	s_movk_i32 s8, 0x5c0
	v_cmp_gt_i32_e32 vcc, s8, v131
	s_and_saveexec_b64 s[10:11], vcc
	s_cbranch_execz .LBB0_908
	v_add_u32_e32 v2, 0xb00, v131
	v_ashrrev_i32_e32 v2, 6, v2
	v_add_u32_e32 v2, s22, v2
	v_cmp_le_i32_e32 vcc, s16, v2
	v_cmp_gt_i32_e64 s[8:9], s17, v2
	s_and_b64 s[24:25], vcc, s[8:9]
	v_mov_b32_e32 v15, 0
	s_and_saveexec_b64 s[8:9], s[24:25]
	s_cbranch_execz .LBB0_907
	v_mov_b32_e32 v3, v169
	v_lshl_add_u64 v[2:3], s[6:7], 0, v[2:3]
	v_lshlrev_b64 v[2:3], 10, v[2:3]
	v_lshl_add_u64 v[2:3], v[0:1], 0, v[2:3]
	global_load_ushort v15, v[2:3], off

; DI float bf2f(u16 v) { return __uint_as_float(((unsigned)v) << 16); }
; DI void lru_job(const Params& P, int layer, int b, int chunk, int blk, int mode, char* smem, const LruConst& C) {
;     ...
;   for (int it = 0; it < 17; ++it) {
;     int idx = tid + it * 256;
;     int rr = idx >> 6, dd = idx & 63, pp = p0 - 1 + rr;
;     if (idx < 67 * 64) xs[idx] = (pp >= seg_lo && pp < seg_hi) ? bf2f(XA[((size_t)b * TB + pp) * 512 + blk * 64 + dd]) : 0.f;
;   }
.LBB0_908:
	s_or_b64 exec, exec, s[10:11]
	s_movk_i32 s8, 0x4c0
	v_cmp_gt_i32_e32 vcc, s8, v131
	s_and_saveexec_b64 s[10:11], vcc
	s_cbranch_execz .LBB0_912
	v_add_u32_e32 v2, 0xc00, v131
	v_ashrrev_i32_e32 v2, 6, v2
	v_add_u32_e32 v2, s22, v2
	v_cmp_le_i32_e32 vcc, s16, v2
	v_cmp_gt_i32_e64 s[8:9], s17, v2
	s_and_b64 s[24:25], vcc, s[8:9]
	v_mov_b32_e32 v16, 0
	s_and_saveexec_b64 s[8:9], s[24:25]
	s_cbranch_execz .LBB0_911
	v_mov_b32_e32 v3, v169
	v_lshl_add_u64 v[2:3], s[6:7], 0, v[2:3]
	v_lshlrev_b64 v[2:3], 10, v[2:3]
	v_lshl_add_u64 v[2:3], v[0:1], 0, v[2:3]
	global_load_ushort v16, v[2:3], off

; DI float bf2f(u16 v) { return __uint_as_float(((unsigned)v) << 16); }
; DI void lru_job(const Params& P, int layer, int b, int chunk, int blk, int mode, char* smem, const LruConst& C) {
;     ...
;   for (int it = 0; it < 17; ++it) {
;     int idx = tid + it * 256;
;     int rr = idx >> 6, dd = idx & 63, pp = p0 - 1 + rr;
;     if (idx < 67 * 64) xs[idx] = (pp >= seg_lo && pp < seg_hi) ? bf2f(XA[((size_t)b * TB + pp) * 512 + blk * 64 + dd]) : 0.f;
;   }
.LBB0_912:
	s_or_b64 exec, exec, s[10:11]
	s_movk_i32 s8, 0x3c0
	v_cmp_gt_i32_e32 vcc, s8, v131
	s_and_saveexec_b64 s[10:11], vcc
	s_cbranch_execz .LBB0_916
	v_add_u32_e32 v2, 0xd00, v131
	v_ashrrev_i32_e32 v2, 6, v2
	v_add_u32_e32 v2, s22, v2
	v_cmp_le_i32_e32 vcc, s16, v2
	v_cmp_gt_i32_e64 s[8:9], s17, v2
	s_and_b64 s[24:25], vcc, s[8:9]
	v_mov_b32_e32 v17, 0
	s_and_saveexec_b64 s[8:9], s[24:25]
	s_cbranch_execz .LBB0_915
	v_mov_b32_e32 v3, v169
	v_lshl_add_u64 v[2:3], s[6:7], 0, v[2:3]
	v_lshlrev_b64 v[2:3], 10, v[2:3]
	v_lshl_add_u64 v[2:3], v[0:1], 0, v[2:3]
	global_load_ushort v17, v[2:3], off

; DI float bf2f(u16 v) { return __uint_as_float(((unsigned)v) << 16); }
; DI void lru_job(const Params& P, int layer, int b, int chunk, int blk, int mode, char* smem, const LruConst& C) {
;     ...
;   for (int it = 0; it < 17; ++it) {
;     int idx = tid + it * 256;
;     int rr = idx >> 6, dd = idx & 63, pp = p0 - 1 + rr;
;     if (idx < 67 * 64) xs[idx] = (pp >= seg_lo && pp < seg_hi) ? bf2f(XA[((size_t)b * TB + pp) * 512 + blk * 64 + dd]) : 0.f;
;   }
.LBB0_916:
	s_or_b64 exec, exec, s[10:11]
	s_movk_i32 s8, 0x2c0
	v_cmp_gt_i32_e32 vcc, s8, v131
	s_and_saveexec_b64 s[10:11], vcc
	s_cbranch_execz .LBB0_920
	v_add_u32_e32 v2, 0xe00, v131
	v_ashrrev_i32_e32 v2, 6, v2
	v_add_u32_e32 v2, s22, v2
	v_cmp_le_i32_e32 vcc, s16, v2
	v_cmp_gt_i32_e64 s[8:9], s17, v2
	s_and_b64 s[24:25], vcc, s[8:9]
	v_mov_b32_e32 v18, 0
	s_and_saveexec_b64 s[8:9], s[24:25]
	s_cbranch_execz .LBB0_919
	v_mov_b32_e32 v3, v169
	v_lshl_add_u64 v[2:3], s[6:7], 0, v[2:3]
	v_lshlrev_b64 v[2:3], 10, v[2:3]
	v_lshl_add_u64 v[2:3], v[0:1], 0, v[2:3]
	global_load_ushort v18, v[2:3], off

; DI float bf2f(u16 v) { return __uint_as_float(((unsigned)v) << 16); }
; DI void lru_job(const Params& P, int layer, int b, int chunk, int blk, int mode, char* smem, const LruConst& C) {
;     ...
;   for (int it = 0; it < 17; ++it) {
;     int idx = tid + it * 256;
;     int rr = idx >> 6, dd = idx & 63, pp = p0 - 1 + rr;
;     if (idx < 67 * 64) xs[idx] = (pp >= seg_lo && pp < seg_hi) ? bf2f(XA[((size_t)b * TB + pp) * 512 + blk * 64 + dd]) : 0.f;
;   }
.LBB0_920:
	s_or_b64 exec, exec, s[10:11]
	s_movk_i32 s8, 0x1c0
	v_cmp_gt_i32_e32 vcc, s8, v131
	s_and_saveexec_b64 s[10:11], vcc
	s_cbranch_execz .LBB0_924
	v_add_u32_e32 v2, 0xf00, v131
	v_ashrrev_i32_e32 v2, 6, v2
	v_add_u32_e32 v2, s22, v2
	v_cmp_le_i32_e32 vcc, s16, v2
	v_cmp_gt_i32_e64 s[8:9], s17, v2
	s_and_b64 s[24:25], vcc, s[8:9]
	v_mov_b32_e32 v19, 0
	s_and_saveexec_b64 s[8:9], s[24:25]
	s_cbranch_execz .LBB0_923
	v_mov_b32_e32 v3, v169
	v_lshl_add_u64 v[2:3], s[6:7], 0, v[2:3]
	v_lshlrev_b64 v[2:3], 10, v[2:3]
	v_lshl_add_u64 v[2:3], v[0:1], 0, v[2:3]
	global_load_ushort v19, v[2:3], off

; DI float bf2f(u16 v) { return __uint_as_float(((unsigned)v) << 16); }
; DI void lru_job(const Params& P, int layer, int b, int chunk, int blk, int mode, char* smem, const LruConst& C) {
;     ...
;   for (int it = 0; it < 17; ++it) {
;     int idx = tid + it * 256;
;     int rr = idx >> 6, dd = idx & 63, pp = p0 - 1 + rr;
;     if (idx < 67 * 64) xs[idx] = (pp >= seg_lo && pp < seg_hi) ? bf2f(XA[((size_t)b * TB + pp) * 512 + blk * 64 + dd]) : 0.f;
;   }
.LBB0_924:
	s_or_b64 exec, exec, s[10:11]
	s_waitcnt vmcnt(0)
	v_lshlrev_b32_e32 v2, 2, v131
	v_lshlrev_b32_e32 v3, 16, v4
	ds_write_b32 v2, v3 offset:9216
	v_lshlrev_b32_e32 v3, 16, v5
	ds_write_b32 v2, v3 offset:10240
	v_lshlrev_b32_e32 v3, 16, v6
	ds_write_b32 v2, v3 offset:11264
	v_lshlrev_b32_e32 v3, 16, v7
	ds_write_b32 v2, v3 offset:12288
	v_lshlrev_b32_e32 v3, 16, v8
	ds_write_b32 v2, v3 offset:13312
	v_lshlrev_b32_e32 v3, 16, v9
	ds_write_b32 v2, v3 offset:14336
	v_lshlrev_b32_e32 v3, 16, v10
	ds_write_b32 v2, v3 offset:15360
	v_lshlrev_b32_e32 v3, 16, v11
	ds_write_b32 v2, v3 offset:16384
	v_lshlrev_b32_e32 v3, 16, v12
	ds_write_b32 v2, v3 offset:17408
	v_lshlrev_b32_e32 v3, 16, v13
	ds_write_b32 v2, v3 offset:18432
	v_lshlrev_b32_e32 v3, 16, v14
	ds_write_b32 v2, v3 offset:19456
	v_lshlrev_b32_e32 v3, 16, v15
	ds_write_b32 v2, v3 offset:20480
	v_lshlrev_b32_e32 v3, 16, v16
	ds_write_b32 v2, v3 offset:21504
	v_lshlrev_b32_e32 v3, 16, v17
	ds_write_b32 v2, v3 offset:22528
	v_lshlrev_b32_e32 v3, 16, v18
	ds_write_b32 v2, v3 offset:23552
	v_lshlrev_b32_e32 v3, 16, v19
	ds_write_b32 v2, v3 offset:24576
	s_movk_i32 s8, 0xc0
	v_cmp_gt_i32_e32 vcc, s8, v131
	s_and_saveexec_b64 s[10:11], vcc
	s_cbranch_execz .LBB0_928
	v_add_u32_e32 v2, 0x1000, v131
	v_ashrrev_i32_e32 v2, 6, v2
	v_add_u32_e32 v2, s22, v2
	v_cmp_le_i32_e32 vcc, s16, v2
	v_cmp_gt_i32_e64 s[8:9], s17, v2
	s_and_b64 s[16:17], vcc, s[8:9]
	v_mov_b32_e32 v3, 0
	s_and_saveexec_b64 s[8:9], s[16:17]
	s_cbranch_execz .LBB0_927
	v_mov_b32_e32 v3, v169
	v_lshl_add_u64 v[2:3], s[6:7], 0, v[2:3]
	v_lshlrev_b64 v[2:3], 10, v[2:3]
	v_lshl_add_u64 v[0:1], v[0:1], 0, v[2:3]
	global_load_ushort v0, v[0:1], off
	s_waitcnt vmcnt(0)
	v_lshlrev_b32_e32 v3, 16, v0
